# neighbour-team wait polls up to four team counters in parallel
# baseline (speedup 1.0000x reference)
.Ltb_go:
	v_readlane_b32 s1, v243, 19
	s_mov_b32 s34, 0
	s_cmp_eq_u32 s1, 2
	s_cselect_b32 s34, 9, s34
	s_cselect_b32 s35, 5958, s35
	s_cmp_eq_u32 s1, 5
	s_cselect_b32 s34, 4, s34
	s_cselect_b32 s35, 7282, s35
	s_cmp_eq_u32 s1, 8
	s_cselect_b32 s34, 11, s34
	s_cselect_b32 s35, 16384, s35
	s_cmp_eq_u32 s1, 12
	s_cselect_b32 s34, 12, s34
	s_cselect_b32 s35, 5958, s35
	s_cmp_eq_u32 s1, 15
	s_cselect_b32 s34, 4, s34
	s_cselect_b32 s35, 5462, s35
	s_cmp_eq_u32 s1, 18
	s_cselect_b32 s34, 11, s34
	s_cselect_b32 s35, 16384, s35
	s_cmp_eq_u32 s34, 0
	s_cbranch_scc1 .LBB0_7
	v_readlane_b32 s1, v243, 16
	s_and_b32 s28, s1, 7
	s_lshl_b32 s28, s28, 3
	s_bfe_u32 s29, s1, 0x30003
	s_add_i32 s28, s28, s29
	s_mul_i32 s29, s28, s34
	s_add_i32 s1, s29, s34
	s_add_i32 s1, s1, -1
	s_mul_i32 s29, s29, s35
	s_lshr_b32 s28, s29, 16
	s_mul_i32 s1, s1, s35
	s_lshr_b32 s1, s1, 16
	s_min_u32 s1, s1, 63
	s_add_u32 s34, s96, 0xeb12d00
	s_addc_u32 s35, s97, 0
	s_min_u32 s29, s28, s1
	s_lshr_b32 vcc_lo, s29, 3
	s_and_b32 s29, s29, 7
	s_lshl_b32 s29, s29, 3
	s_add_i32 s29, s29, vcc_lo
	s_lshl_b32 s29, s29, 5
	v_mov_b32_e32 v3, s29
	s_add_i32 s28, s28, 1
	s_min_u32 s29, s28, s1
	s_lshr_b32 vcc_lo, s29, 3
	s_and_b32 s29, s29, 7
	s_lshl_b32 s29, s29, 3
	s_add_i32 s29, s29, vcc_lo
	s_lshl_b32 s29, s29, 5
	v_mov_b32_e32 v4, s29
	s_add_i32 s28, s28, 1
	s_min_u32 s29, s28, s1
	s_lshr_b32 vcc_lo, s29, 3
	s_and_b32 s29, s29, 7
	s_lshl_b32 s29, s29, 3
	s_add_i32 s29, s29, vcc_lo
	s_lshl_b32 s29, s29, 5
	v_mov_b32_e32 v5, s29
	s_add_i32 s28, s28, 1
	s_min_u32 s29, s28, s1
	s_lshr_b32 vcc_lo, s29, 3
	s_and_b32 s29, s29, 7
	s_lshl_b32 s29, s29, 3
	s_add_i32 s29, s29, vcc_lo
	s_lshl_b32 s29, s29, 5
	v_mov_b32_e32 v6, s29
.Ltb_nb_poll:
	global_load_dword v7, v3, s[34:35] sc1
	global_load_dword v8, v4, s[34:35] sc1
	global_load_dword v9, v5, s[34:35] sc1
	global_load_dword v10, v6, s[34:35] sc1
	s_waitcnt vmcnt(0)
	v_min_u32_e32 v7, v7, v8
	v_min_u32_e32 v9, v9, v10
	v_min_u32_e32 v7, v7, v9
	s_nop 0
	v_readfirstlane_b32 s29, v7
	s_cmp_ge_u32 s29, s0
	s_cbranch_scc1 .LBB0_7
	s_sleep 1
	s_branch .Ltb_nb_poll
	s_branch .LBB0_7
